# combo2 + NSA near-path position-bias lookups done 4 at a time (one LDS wait per 4, v_cndmask select) instead of a predicated branch + LDS round trip each
# speedup vs baseline: 1.0042x; 1.0019x over previous
.LBB0_931:
	v_mov_b32_e32 v250, 0xff800000
	v_min_u32_e32 v0, 0x7f, v149
	v_lshl_add_u32 v0, v0, 4, v142
	ds_read_b32 v0, v0
	v_add_u32_e32 v247, -1, v149
	v_min_u32_e32 v1, 0x7f, v247
	v_lshl_add_u32 v1, v1, 4, v142
	ds_read_b32 v1, v1
	v_add_u32_e32 v248, -2, v149
	v_min_u32_e32 v2, 0x7f, v248
	v_lshl_add_u32 v2, v2, 4, v142
	ds_read_b32 v2, v2
	v_add_u32_e32 v249, -3, v149
	v_min_u32_e32 v3, 0x7f, v249
	v_lshl_add_u32 v3, v3, 4, v142
	ds_read_b32 v3, v3
	s_waitcnt lgkmcnt(0)
	v_cmp_lt_i32_e32 vcc, -1, v149
	s_and_b64 vcc, s[2:3], vcc
	v_fmac_f32_e32 v0, 0x3e38aa3b, v128
	v_cndmask_b32_e32 v0, v250, v0, vcc
	v_cmp_lt_i32_e32 vcc, -1, v247
	s_and_b64 vcc, s[2:3], vcc
	v_fmac_f32_e32 v1, 0x3e38aa3b, v129
	v_cndmask_b32_e32 v1, v250, v1, vcc
	v_cmp_lt_i32_e32 vcc, -1, v248
	s_and_b64 vcc, s[2:3], vcc
	v_fmac_f32_e32 v2, 0x3e38aa3b, v130
	v_cndmask_b32_e32 v2, v250, v2, vcc
	v_cmp_lt_i32_e32 vcc, -1, v249
	s_and_b64 vcc, s[2:3], vcc
	v_fmac_f32_e32 v3, 0x3e38aa3b, v131
	v_cndmask_b32_e32 v3, v250, v3, vcc
	v_add_u32_e32 v246, -16, v149
	v_min_u32_e32 v4, 0x7f, v246
	v_lshl_add_u32 v4, v4, 4, v142
	ds_read_b32 v4, v4
	v_subrev_u32_e32 v247, 17, v149
	v_min_u32_e32 v5, 0x7f, v247
	v_lshl_add_u32 v5, v5, 4, v142
	ds_read_b32 v5, v5
	v_subrev_u32_e32 v248, 18, v149
	v_min_u32_e32 v6, 0x7f, v248
	v_lshl_add_u32 v6, v6, 4, v142
	ds_read_b32 v6, v6
	v_subrev_u32_e32 v249, 19, v149
	v_min_u32_e32 v7, 0x7f, v249
	v_lshl_add_u32 v7, v7, 4, v142
	ds_read_b32 v7, v7
	s_waitcnt lgkmcnt(0)
	v_cmp_lt_i32_e32 vcc, -1, v246
	s_and_b64 vcc, s[2:3], vcc
	v_fmac_f32_e32 v4, 0x3e38aa3b, v124
	v_cndmask_b32_e32 v4, v250, v4, vcc
	v_cmp_lt_i32_e32 vcc, -1, v247
	s_and_b64 vcc, s[2:3], vcc
	v_fmac_f32_e32 v5, 0x3e38aa3b, v125
	v_cndmask_b32_e32 v5, v250, v5, vcc
	v_cmp_lt_i32_e32 vcc, -1, v248
	s_and_b64 vcc, s[2:3], vcc
	v_fmac_f32_e32 v6, 0x3e38aa3b, v126
	v_cndmask_b32_e32 v6, v250, v6, vcc
	v_cmp_lt_i32_e32 vcc, -1, v249
	s_and_b64 vcc, s[2:3], vcc
	v_fmac_f32_e32 v7, 0x3e38aa3b, v127
	v_cndmask_b32_e32 v7, v250, v7, vcc
	v_subrev_u32_e32 v246, 32, v149
	v_min_u32_e32 v8, 0x7f, v246
	v_lshl_add_u32 v8, v8, 4, v142
	ds_read_b32 v8, v8
	v_subrev_u32_e32 v247, 33, v149
	v_min_u32_e32 v9, 0x7f, v247
	v_lshl_add_u32 v9, v9, 4, v142
	ds_read_b32 v9, v9
	v_subrev_u32_e32 v248, 34, v149
	v_min_u32_e32 v10, 0x7f, v248
	v_lshl_add_u32 v10, v10, 4, v142
	ds_read_b32 v10, v10
	v_subrev_u32_e32 v249, 35, v149
	v_min_u32_e32 v11, 0x7f, v249
	v_lshl_add_u32 v11, v11, 4, v142
	ds_read_b32 v11, v11
	s_waitcnt lgkmcnt(0)
	v_cmp_lt_i32_e32 vcc, -1, v246
	s_and_b64 vcc, s[2:3], vcc
	v_fmac_f32_e32 v8, 0x3e38aa3b, v120
	v_cndmask_b32_e32 v8, v250, v8, vcc
	v_cmp_lt_i32_e32 vcc, -1, v247
	s_and_b64 vcc, s[2:3], vcc
	v_fmac_f32_e32 v9, 0x3e38aa3b, v121
	v_cndmask_b32_e32 v9, v250, v9, vcc
	v_cmp_lt_i32_e32 vcc, -1, v248
	s_and_b64 vcc, s[2:3], vcc
	v_fmac_f32_e32 v10, 0x3e38aa3b, v122
	v_cndmask_b32_e32 v10, v250, v10, vcc
	v_cmp_lt_i32_e32 vcc, -1, v249
	s_and_b64 vcc, s[2:3], vcc
	v_fmac_f32_e32 v11, 0x3e38aa3b, v123
	v_cndmask_b32_e32 v11, v250, v11, vcc
	v_subrev_u32_e32 v246, 48, v149
	v_min_u32_e32 v12, 0x7f, v246
	v_lshl_add_u32 v12, v12, 4, v142
	ds_read_b32 v12, v12
	v_subrev_u32_e32 v247, 49, v149
	v_min_u32_e32 v13, 0x7f, v247
	v_lshl_add_u32 v13, v13, 4, v142
	ds_read_b32 v13, v13
	v_subrev_u32_e32 v248, 50, v149
	v_min_u32_e32 v14, 0x7f, v248
	v_lshl_add_u32 v14, v14, 4, v142
	ds_read_b32 v14, v14
	v_subrev_u32_e32 v249, 51, v149
	v_min_u32_e32 v15, 0x7f, v249
	v_lshl_add_u32 v15, v15, 4, v142
	ds_read_b32 v15, v15
	s_waitcnt lgkmcnt(0)
	v_cmp_lt_i32_e32 vcc, -1, v246
	s_and_b64 vcc, s[2:3], vcc
	v_fmac_f32_e32 v12, 0x3e38aa3b, v116
	v_cndmask_b32_e32 v12, v250, v12, vcc
	v_cmp_lt_i32_e32 vcc, -1, v247
	s_and_b64 vcc, s[2:3], vcc
	v_fmac_f32_e32 v13, 0x3e38aa3b, v117
	v_cndmask_b32_e32 v13, v250, v13, vcc
	v_cmp_lt_i32_e32 vcc, -1, v248
	s_and_b64 vcc, s[2:3], vcc
	v_fmac_f32_e32 v14, 0x3e38aa3b, v118
	v_cndmask_b32_e32 v14, v250, v14, vcc
	v_cmp_lt_i32_e32 vcc, -1, v249
	s_and_b64 vcc, s[2:3], vcc
	v_fmac_f32_e32 v15, 0x3e38aa3b, v119
	v_cndmask_b32_e32 v15, v250, v15, vcc
	v_max3_f32 v18, v0, s90, v1
	v_max3_f32 v18, v18, v2, v3
	v_max3_f32 v18, v18, v4, v5
	v_max3_f32 v18, v18, v6, v7
	v_max3_f32 v18, v18, v8, v9
	v_max3_f32 v18, v18, v10, v11
	v_max3_f32 v18, v18, v12, v13
	v_max3_f32 v18, v18, v14, v15
	v_mov_b32_e32 v19, v18
	s_nop 1
	v_permlane16_swap_b32_e32 v18, v19
	v_max_f32_e32 v19, v19, v19
	v_max_f32_e32 v18, v18, v18
	v_max_f32_e32 v18, v18, v19
	v_mov_b32_e32 v19, v18
	s_nop 1
	v_permlane32_swap_b32_e32 v18, v19
	v_max3_f32 v19, v140, v18, v19
	v_cmp_neq_f32_e32 vcc, s90, v19
	s_nop 1
	v_cndmask_b32_e32 v149, 0, v19, vcc
	v_sub_f32_e32 v0, v0, v149
	v_exp_f32_e32 v0, v0
	v_sub_f32_e32 v1, v1, v149
	v_exp_f32_e32 v1, v1
	v_sub_f32_e32 v2, v2, v149
	v_exp_f32_e32 v2, v2
	v_sub_f32_e32 v3, v3, v149
	v_exp_f32_e32 v3, v3
	v_sub_f32_e32 v4, v4, v149
	v_add_f32_e32 v148, 0, v0
	v_exp_f32_e32 v4, v4
	v_sub_f32_e32 v5, v5, v149
	v_add_f32_e32 v148, v1, v148
	v_exp_f32_e32 v5, v5
	v_sub_f32_e32 v6, v6, v149
	v_add_f32_e32 v148, v2, v148
	v_exp_f32_e32 v6, v6
	v_sub_f32_e32 v7, v7, v149
	v_add_f32_e32 v148, v3, v148
	v_exp_f32_e32 v7, v7
	v_sub_f32_e32 v8, v8, v149
	v_add_f32_e32 v148, v4, v148
	v_exp_f32_e32 v8, v8
	v_sub_f32_e32 v9, v9, v149
	v_add_f32_e32 v148, v5, v148
	v_exp_f32_e32 v9, v9
	v_sub_f32_e32 v10, v10, v149
	v_add_f32_e32 v148, v6, v148
	v_exp_f32_e32 v10, v10
	v_sub_f32_e32 v11, v11, v149
	v_add_f32_e32 v148, v7, v148
	v_exp_f32_e32 v11, v11
	v_sub_f32_e32 v12, v12, v149
	v_add_f32_e32 v148, v8, v148
	v_exp_f32_e32 v12, v12
	v_sub_f32_e32 v13, v13, v149
	v_add_f32_e32 v148, v9, v148
	v_exp_f32_e32 v13, v13
	v_sub_f32_e32 v14, v14, v149
	v_sub_f32_e32 v18, v140, v149
	v_add_f32_e32 v148, v10, v148
	v_exp_f32_e32 v14, v14
	v_exp_f32_e32 v18, v18
	v_add_f32_e32 v148, v11, v148
	v_add_f32_e32 v148, v12, v148
	v_add_f32_e32 v148, v13, v148
	v_add_f32_e32 v148, v14, v148
	v_sub_f32_e32 v15, v15, v149
	s_branch .LBB0_921

.LBB0_965:
	v_mov_b32_e32 v250, 0xff800000
	v_min_u32_e32 v0, 0x7f, v150
	v_lshl_add_u32 v0, v0, 4, v142
	ds_read_b32 v0, v0
	v_add_u32_e32 v247, -1, v150
	v_min_u32_e32 v1, 0x7f, v247
	v_lshl_add_u32 v1, v1, 4, v142
	ds_read_b32 v1, v1
	v_add_u32_e32 v248, -2, v150
	v_min_u32_e32 v2, 0x7f, v248
	v_lshl_add_u32 v2, v2, 4, v142
	ds_read_b32 v2, v2
	v_add_u32_e32 v249, -3, v150
	v_min_u32_e32 v3, 0x7f, v249
	v_lshl_add_u32 v3, v3, 4, v142
	ds_read_b32 v3, v3
	s_waitcnt lgkmcnt(0)
	v_cmp_lt_i32_e32 vcc, -1, v150
	s_and_b64 vcc, s[2:3], vcc
	v_fmac_f32_e32 v0, 0x3e38aa3b, v128
	v_cndmask_b32_e32 v0, v250, v0, vcc
	v_cmp_lt_i32_e32 vcc, -1, v247
	s_and_b64 vcc, s[2:3], vcc
	v_fmac_f32_e32 v1, 0x3e38aa3b, v129
	v_cndmask_b32_e32 v1, v250, v1, vcc
	v_cmp_lt_i32_e32 vcc, -1, v248
	s_and_b64 vcc, s[2:3], vcc
	v_fmac_f32_e32 v2, 0x3e38aa3b, v130
	v_cndmask_b32_e32 v2, v250, v2, vcc
	v_cmp_lt_i32_e32 vcc, -1, v249
	s_and_b64 vcc, s[2:3], vcc
	v_fmac_f32_e32 v3, 0x3e38aa3b, v131
	v_cndmask_b32_e32 v3, v250, v3, vcc
	v_add_u32_e32 v246, -16, v150
	v_min_u32_e32 v4, 0x7f, v246
	v_lshl_add_u32 v4, v4, 4, v142
	ds_read_b32 v4, v4
	v_subrev_u32_e32 v247, 17, v150
	v_min_u32_e32 v5, 0x7f, v247
	v_lshl_add_u32 v5, v5, 4, v142
	ds_read_b32 v5, v5
	v_subrev_u32_e32 v248, 18, v150
	v_min_u32_e32 v6, 0x7f, v248
	v_lshl_add_u32 v6, v6, 4, v142
	ds_read_b32 v6, v6
	v_subrev_u32_e32 v249, 19, v150
	v_min_u32_e32 v7, 0x7f, v249
	v_lshl_add_u32 v7, v7, 4, v142
	ds_read_b32 v7, v7
	s_waitcnt lgkmcnt(0)
	v_cmp_lt_i32_e32 vcc, -1, v246
	s_and_b64 vcc, s[2:3], vcc
	v_fmac_f32_e32 v4, 0x3e38aa3b, v124
	v_cndmask_b32_e32 v4, v250, v4, vcc
	v_cmp_lt_i32_e32 vcc, -1, v247
	s_and_b64 vcc, s[2:3], vcc
	v_fmac_f32_e32 v5, 0x3e38aa3b, v125
	v_cndmask_b32_e32 v5, v250, v5, vcc
	v_cmp_lt_i32_e32 vcc, -1, v248
	s_and_b64 vcc, s[2:3], vcc
	v_fmac_f32_e32 v6, 0x3e38aa3b, v126
	v_cndmask_b32_e32 v6, v250, v6, vcc
	v_cmp_lt_i32_e32 vcc, -1, v249
	s_and_b64 vcc, s[2:3], vcc
	v_fmac_f32_e32 v7, 0x3e38aa3b, v127
	v_cndmask_b32_e32 v7, v250, v7, vcc
	v_subrev_u32_e32 v246, 32, v150
	v_min_u32_e32 v8, 0x7f, v246
	v_lshl_add_u32 v8, v8, 4, v142
	ds_read_b32 v8, v8
	v_subrev_u32_e32 v247, 33, v150
	v_min_u32_e32 v9, 0x7f, v247
	v_lshl_add_u32 v9, v9, 4, v142
	ds_read_b32 v9, v9
	v_subrev_u32_e32 v248, 34, v150
	v_min_u32_e32 v10, 0x7f, v248
	v_lshl_add_u32 v10, v10, 4, v142
	ds_read_b32 v10, v10
	v_subrev_u32_e32 v249, 35, v150
	v_min_u32_e32 v11, 0x7f, v249
	v_lshl_add_u32 v11, v11, 4, v142
	ds_read_b32 v11, v11
	s_waitcnt lgkmcnt(0)
	v_cmp_lt_i32_e32 vcc, -1, v246
	s_and_b64 vcc, s[2:3], vcc
	v_fmac_f32_e32 v8, 0x3e38aa3b, v120
	v_cndmask_b32_e32 v8, v250, v8, vcc
	v_cmp_lt_i32_e32 vcc, -1, v247
	s_and_b64 vcc, s[2:3], vcc
	v_fmac_f32_e32 v9, 0x3e38aa3b, v121
	v_cndmask_b32_e32 v9, v250, v9, vcc
	v_cmp_lt_i32_e32 vcc, -1, v248
	s_and_b64 vcc, s[2:3], vcc
	v_fmac_f32_e32 v10, 0x3e38aa3b, v122
	v_cndmask_b32_e32 v10, v250, v10, vcc
	v_cmp_lt_i32_e32 vcc, -1, v249
	s_and_b64 vcc, s[2:3], vcc
	v_fmac_f32_e32 v11, 0x3e38aa3b, v123
	v_cndmask_b32_e32 v11, v250, v11, vcc
	v_subrev_u32_e32 v246, 48, v150
	v_min_u32_e32 v12, 0x7f, v246
	v_lshl_add_u32 v12, v12, 4, v142
	ds_read_b32 v12, v12
	v_subrev_u32_e32 v247, 49, v150
	v_min_u32_e32 v13, 0x7f, v247
	v_lshl_add_u32 v13, v13, 4, v142
	ds_read_b32 v13, v13
	v_subrev_u32_e32 v248, 50, v150
	v_min_u32_e32 v14, 0x7f, v248
	v_lshl_add_u32 v14, v14, 4, v142
	ds_read_b32 v14, v14
	v_subrev_u32_e32 v249, 51, v150
	v_min_u32_e32 v15, 0x7f, v249
	v_lshl_add_u32 v15, v15, 4, v142
	ds_read_b32 v15, v15
	s_waitcnt lgkmcnt(0)
	v_cmp_lt_i32_e32 vcc, -1, v246
	s_and_b64 vcc, s[2:3], vcc
	v_fmac_f32_e32 v12, 0x3e38aa3b, v116
	v_cndmask_b32_e32 v12, v250, v12, vcc
	v_cmp_lt_i32_e32 vcc, -1, v247
	s_and_b64 vcc, s[2:3], vcc
	v_fmac_f32_e32 v13, 0x3e38aa3b, v117
	v_cndmask_b32_e32 v13, v250, v13, vcc
	v_cmp_lt_i32_e32 vcc, -1, v248
	s_and_b64 vcc, s[2:3], vcc
	v_fmac_f32_e32 v14, 0x3e38aa3b, v118
	v_cndmask_b32_e32 v14, v250, v14, vcc
	v_cmp_lt_i32_e32 vcc, -1, v249
	s_and_b64 vcc, s[2:3], vcc
	v_fmac_f32_e32 v15, 0x3e38aa3b, v119
	v_cndmask_b32_e32 v15, v250, v15, vcc
	v_max3_f32 v140, v0, s90, v1
	v_max3_f32 v140, v140, v2, v3
	v_max3_f32 v140, v140, v4, v5
	v_max3_f32 v140, v140, v6, v7
	v_max3_f32 v140, v140, v8, v9
	v_max3_f32 v140, v140, v10, v11
	v_max3_f32 v140, v140, v12, v13
	v_max3_f32 v140, v140, v14, v15
	v_mov_b32_e32 v150, v140
	s_nop 1
	v_permlane16_swap_b32_e32 v140, v150
	v_max_f32_e32 v150, v150, v150
	v_max_f32_e32 v140, v140, v140
	v_max_f32_e32 v140, v140, v150
	v_mov_b32_e32 v150, v140
	s_nop 1
	v_permlane32_swap_b32_e32 v140, v150
	v_max3_f32 v151, v147, v140, v150
	v_cmp_neq_f32_e32 vcc, s90, v151
	s_nop 1
	v_cndmask_b32_e32 v150, 0, v151, vcc
	v_sub_f32_e32 v0, v0, v150
	v_exp_f32_e32 v0, v0
	v_sub_f32_e32 v1, v1, v150
	v_exp_f32_e32 v1, v1
	v_sub_f32_e32 v2, v2, v150
	v_exp_f32_e32 v2, v2
	v_sub_f32_e32 v3, v3, v150
	v_exp_f32_e32 v3, v3
	v_sub_f32_e32 v4, v4, v150
	v_add_f32_e32 v152, 0, v0
	v_exp_f32_e32 v4, v4
	v_sub_f32_e32 v5, v5, v150
	v_add_f32_e32 v152, v1, v152
	v_exp_f32_e32 v5, v5
	v_sub_f32_e32 v6, v6, v150
	v_add_f32_e32 v152, v2, v152
	v_exp_f32_e32 v6, v6
	v_sub_f32_e32 v7, v7, v150
	v_add_f32_e32 v152, v3, v152
	v_exp_f32_e32 v7, v7
	v_sub_f32_e32 v8, v8, v150
	v_add_f32_e32 v152, v4, v152
	v_exp_f32_e32 v8, v8
	v_sub_f32_e32 v9, v9, v150
	v_add_f32_e32 v152, v5, v152
	v_exp_f32_e32 v9, v9
	v_sub_f32_e32 v10, v10, v150
	v_add_f32_e32 v152, v6, v152
	v_exp_f32_e32 v10, v10
	v_sub_f32_e32 v11, v11, v150
	v_add_f32_e32 v152, v7, v152
	v_exp_f32_e32 v11, v11
	v_sub_f32_e32 v12, v12, v150
	v_add_f32_e32 v152, v8, v152
	v_exp_f32_e32 v12, v12
	v_sub_f32_e32 v13, v13, v150
	v_add_f32_e32 v152, v9, v152
	v_exp_f32_e32 v13, v13
	v_sub_f32_e32 v14, v14, v150
	v_sub_f32_e32 v140, v147, v150
	v_add_f32_e32 v152, v10, v152
	v_exp_f32_e32 v14, v14
	v_exp_f32_e32 v140, v140
	v_add_f32_e32 v152, v11, v152
	v_add_f32_e32 v152, v12, v152
	v_add_f32_e32 v152, v13, v152
	v_add_f32_e32 v160, v14, v152
	v_sub_f32_e32 v15, v15, v150
	s_branch .LBB0_927
